# v39: v37 + GEMM tiles after the first skip the 128 accumulator clears: the peeled first K-step's MFMAs take the inline constant 0 as C
# speedup vs baseline: 1.0071x; 1.0012x over previous
.LBB0_63:
	s_add_u32 s40, s40, 0x80
	s_addc_u32 s41, s41, 0
	s_add_u32 vcc_lo, s42, 0x100
	s_addc_u32 vcc_hi, s43, 0
	s_mov_b32 s42, 0
	s_cmp_eq_u32 s85, 1
	s_cbranch_scc0 .Lmy_peel
	v_mov_b32_e32 v0, 0
	v_mov_b32_e32 v1, v0
	v_mov_b32_e32 v2, v0
	v_mov_b32_e32 v3, v0
	v_mov_b32_e32 v4, v0
	v_mov_b32_e32 v5, v0
	v_mov_b32_e32 v6, v0
	v_mov_b32_e32 v7, v0
	v_mov_b32_e32 v16, v0
	v_mov_b32_e32 v17, v0
	v_mov_b32_e32 v18, v0
	v_mov_b32_e32 v19, v0
	v_mov_b32_e32 v20, v0
	v_mov_b32_e32 v21, v0
	v_mov_b32_e32 v22, v0
	v_mov_b32_e32 v23, v0
	v_mov_b32_e32 v32, v0
	v_mov_b32_e32 v33, v0
	v_mov_b32_e32 v34, v0
	v_mov_b32_e32 v35, v0
	v_mov_b32_e32 v36, v0
	v_mov_b32_e32 v37, v0
	v_mov_b32_e32 v38, v0
	v_mov_b32_e32 v39, v0
	v_mov_b32_e32 v48, v0
	v_mov_b32_e32 v49, v0
	v_mov_b32_e32 v50, v0
	v_mov_b32_e32 v51, v0
	v_mov_b32_e32 v52, v0
	v_mov_b32_e32 v53, v0
	v_mov_b32_e32 v54, v0
	v_mov_b32_e32 v55, v0
	v_mov_b32_e32 v8, v0
	v_mov_b32_e32 v9, v0
	v_mov_b32_e32 v10, v0
	v_mov_b32_e32 v11, v0
	v_mov_b32_e32 v12, v0
	v_mov_b32_e32 v13, v0
	v_mov_b32_e32 v14, v0
	v_mov_b32_e32 v15, v0
	v_mov_b32_e32 v24, v0
	v_mov_b32_e32 v25, v0
	v_mov_b32_e32 v26, v0
	v_mov_b32_e32 v27, v0
	v_mov_b32_e32 v28, v0
	v_mov_b32_e32 v29, v0
	v_mov_b32_e32 v30, v0
	v_mov_b32_e32 v31, v0
	v_mov_b32_e32 v40, v0
	v_mov_b32_e32 v41, v0
	v_mov_b32_e32 v42, v0
	v_mov_b32_e32 v43, v0
	v_mov_b32_e32 v44, v0
	v_mov_b32_e32 v45, v0
	v_mov_b32_e32 v46, v0
	v_mov_b32_e32 v47, v0
	v_mov_b32_e32 v56, v0
	v_mov_b32_e32 v57, v0
	v_mov_b32_e32 v58, v0
	v_mov_b32_e32 v59, v0
	v_mov_b32_e32 v60, v0
	v_mov_b32_e32 v61, v0
	v_mov_b32_e32 v62, v0
	v_mov_b32_e32 v63, v0
	v_mov_b32_e32 v64, v0
	v_mov_b32_e32 v65, v0
	v_mov_b32_e32 v66, v0
	v_mov_b32_e32 v67, v0
	v_mov_b32_e32 v68, v0
	v_mov_b32_e32 v69, v0
	v_mov_b32_e32 v70, v0
	v_mov_b32_e32 v71, v0
	v_mov_b32_e32 v80, v0
	v_mov_b32_e32 v81, v0
	v_mov_b32_e32 v82, v0
	v_mov_b32_e32 v83, v0
	v_mov_b32_e32 v84, v0
	v_mov_b32_e32 v85, v0
	v_mov_b32_e32 v86, v0
	v_mov_b32_e32 v87, v0
	v_mov_b32_e32 v96, v0
	v_mov_b32_e32 v97, v0
	v_mov_b32_e32 v98, v0
	v_mov_b32_e32 v99, v0
	v_mov_b32_e32 v100, v0
	v_mov_b32_e32 v101, v0
	v_mov_b32_e32 v102, v0
	v_mov_b32_e32 v103, v0
	v_mov_b32_e32 v112, v0
	v_mov_b32_e32 v113, v0
	v_mov_b32_e32 v114, v0
	v_mov_b32_e32 v115, v0
	v_mov_b32_e32 v116, v0
	v_mov_b32_e32 v117, v0
	v_mov_b32_e32 v118, v0
	v_mov_b32_e32 v119, v0
	v_mov_b32_e32 v72, v0
	v_mov_b32_e32 v73, v0
	v_mov_b32_e32 v74, v0
	v_mov_b32_e32 v75, v0
	v_mov_b32_e32 v76, v0
	v_mov_b32_e32 v77, v0
	v_mov_b32_e32 v78, v0
	v_mov_b32_e32 v79, v0
	v_mov_b32_e32 v88, v0
	v_mov_b32_e32 v89, v0
	v_mov_b32_e32 v90, v0
	v_mov_b32_e32 v91, v0
	v_mov_b32_e32 v92, v0
	v_mov_b32_e32 v93, v0
	v_mov_b32_e32 v94, v0
	v_mov_b32_e32 v95, v0
	v_mov_b32_e32 v104, v0
	v_mov_b32_e32 v105, v0
	v_mov_b32_e32 v106, v0
	v_mov_b32_e32 v107, v0
	v_mov_b32_e32 v108, v0
	v_mov_b32_e32 v109, v0
	v_mov_b32_e32 v110, v0
	v_mov_b32_e32 v111, v0
	v_mov_b32_e32 v120, v0
	v_mov_b32_e32 v121, v0
	v_mov_b32_e32 v122, v0
	v_mov_b32_e32 v123, v0
	v_mov_b32_e32 v124, v0
	v_mov_b32_e32 v125, v0
	v_mov_b32_e32 v126, v0
	v_mov_b32_e32 v127, v0

.Lmy_peel:
	s_add_i32 s33, s42, 2
	s_add_u32 s46, s40, 0x80
	s_addc_u32 s43, s41, 0
	s_add_i32 s80, 0, 0x10000
	s_cmp_eq_u32 s84, s42
	s_cselect_b32 s43, s1, s43
	s_cselect_b32 s42, s0, s46
	s_cselect_b32 s47, s75, vcc_hi
	s_cselect_b32 s46, s74, vcc_lo
	s_add_i32 s5, 0, 0x14000
	v_add_u32_e32 v140, s80, v185
	v_add_u32_e32 v166, s5, v185
	ds_read_b128 v[128:131], v140
	ds_read_b128 v[132:135], v140 offset:1024
	ds_read_b128 v[136:139], v140 offset:2048
	ds_read_b128 v[140:143], v140 offset:3072
	ds_read_b128 v[144:147], v166
	ds_read_b128 v[148:151], v166 offset:1024
	ds_read_b128 v[152:155], v166 offset:2048
	ds_read_b128 v[166:169], v166 offset:3072
	v_lshl_add_u64 v[182:183], s[40:41], 0, v[162:163]
	s_add_i32 m0, s28, 0xc000
	ds_read_b128 v[170:173], v188
	ds_read_b128 v[174:177], v188 offset:1024
	ds_read_b128 v[178:181], v188 offset:2048
	ds_read_b128 v[214:217], v188 offset:3072
	ds_read_b128 v[218:221], v188 offset:4096
	ds_read_b128 v[222:225], v188 offset:5120
	ds_read_b128 v[226:229], v188 offset:6144
	ds_read_b128 v[230:233], v188 offset:7168
	global_load_lds_dwordx4 v[182:183], off
	v_lshl_add_u64 v[182:183], s[40:41], 0, v[164:165]
	s_add_i32 m0, s28, 0xe000
	s_nop 0
	global_load_lds_dwordx4 v[182:183], off
	s_waitcnt vmcnt(24)
	s_waitcnt lgkmcnt(0)
	s_barrier
	s_setprio 1
	s_waitcnt lgkmcnt(0)
	v_mfma_f32_16x16x32_bf16 v[124:127], v[128:131], v[170:173], 0
	v_mfma_f32_16x16x32_bf16 v[120:123], v[136:139], v[170:173], 0
	v_mfma_f32_16x16x32_bf16 v[108:111], v[128:131], v[178:181], 0
	v_mfma_f32_16x16x32_bf16 v[104:107], v[136:139], v[178:181], 0
	v_mfma_f32_16x16x32_bf16 v[92:95], v[128:131], v[218:221], 0
	v_mfma_f32_16x16x32_bf16 v[88:91], v[136:139], v[218:221], 0
	v_mfma_f32_16x16x32_bf16 v[76:79], v[128:131], v[226:229], 0
	v_mfma_f32_16x16x32_bf16 v[72:75], v[136:139], v[226:229], 0
	v_mfma_f32_16x16x32_bf16 v[124:127], v[132:135], v[174:177], v[124:127]
	v_mfma_f32_16x16x32_bf16 v[120:123], v[140:143], v[174:177], v[120:123]
	v_mfma_f32_16x16x32_bf16 v[108:111], v[132:135], v[214:217], v[108:111]
	v_mfma_f32_16x16x32_bf16 v[104:107], v[140:143], v[214:217], v[104:107]
	v_mfma_f32_16x16x32_bf16 v[92:95], v[132:135], v[222:225], v[92:95]
	v_mfma_f32_16x16x32_bf16 v[88:91], v[140:143], v[222:225], v[88:91]
	v_mfma_f32_16x16x32_bf16 v[76:79], v[132:135], v[230:233], v[76:79]
	v_mfma_f32_16x16x32_bf16 v[72:75], v[140:143], v[230:233], v[72:75]
	s_setprio 0
	s_setprio 1
	v_mfma_f32_16x16x32_bf16 v[116:119], v[144:147], v[170:173], 0
	v_mfma_f32_16x16x32_bf16 v[112:115], v[152:155], v[170:173], 0
	v_mfma_f32_16x16x32_bf16 v[100:103], v[144:147], v[178:181], 0
	v_mfma_f32_16x16x32_bf16 v[96:99], v[152:155], v[178:181], 0
	v_mfma_f32_16x16x32_bf16 v[84:87], v[144:147], v[218:221], 0
	v_mfma_f32_16x16x32_bf16 v[80:83], v[152:155], v[218:221], 0
	v_mfma_f32_16x16x32_bf16 v[68:71], v[144:147], v[226:229], 0
	v_mfma_f32_16x16x32_bf16 v[64:67], v[152:155], v[226:229], 0
	v_mfma_f32_16x16x32_bf16 v[116:119], v[148:151], v[174:177], v[116:119]
	v_mfma_f32_16x16x32_bf16 v[112:115], v[166:169], v[174:177], v[112:115]
	v_mfma_f32_16x16x32_bf16 v[100:103], v[148:151], v[214:217], v[100:103]
	v_mfma_f32_16x16x32_bf16 v[96:99], v[166:169], v[214:217], v[96:99]
	v_mfma_f32_16x16x32_bf16 v[84:87], v[148:151], v[222:225], v[84:87]
	v_mfma_f32_16x16x32_bf16 v[80:83], v[166:169], v[222:225], v[80:83]
	v_mfma_f32_16x16x32_bf16 v[68:71], v[148:151], v[230:233], v[68:71]
	v_mfma_f32_16x16x32_bf16 v[64:67], v[166:169], v[230:233], v[64:67]
	s_setprio 0
	s_barrier
	s_add_i32 s80, s80, s27
	v_lshl_add_u64 v[182:183], s[46:47], 0, v[192:193]
	s_mov_b32 m0, s80
	ds_read_b128 v[170:173], v188 offset:16384
	ds_read_b128 v[174:177], v188 offset:17408
	ds_read_b128 v[178:181], v188 offset:18432
	ds_read_b128 v[214:217], v188 offset:19456
	ds_read_b128 v[218:221], v188 offset:20480
	ds_read_b128 v[222:225], v188 offset:21504
	ds_read_b128 v[226:229], v188 offset:22528
	ds_read_b128 v[230:233], v188 offset:23552
	global_load_lds_dwordx4 v[182:183], off
	s_add_i32 m0, s80, 0x2000
	v_lshl_add_u64 v[190:191], s[46:47], 0, v[160:161]
	s_add_u32 s46, s46, s30
	s_addc_u32 s47, s47, 0
	s_add_i32 s5, s5, s27
	global_load_lds_dwordx4 v[190:191], off
	v_lshl_add_u64 v[200:201], s[46:47], 0, v[192:193]
	s_mov_b32 m0, s5
	v_lshl_add_u64 v[234:235], s[46:47], 0, v[160:161]
	global_load_lds_dwordx4 v[200:201], off
	s_add_i32 m0, s5, 0x2000
	v_lshl_add_u64 v[236:237], s[42:43], 0, v[156:157]
	global_load_lds_dwordx4 v[234:235], off
	s_mov_b32 m0, s28
	v_lshl_add_u64 v[238:239], s[42:43], 0, v[158:159]
	global_load_lds_dwordx4 v[236:237], off
	s_mov_b32 m0, s69
	s_nop 0
	global_load_lds_dwordx4 v[238:239], off
	s_waitcnt vmcnt(24)
	s_waitcnt lgkmcnt(0)
	s_barrier
	s_setprio 1
	s_waitcnt lgkmcnt(0)
	v_mfma_f32_16x16x32_bf16 v[60:63], v[128:131], v[170:173], 0
	v_mfma_f32_16x16x32_bf16 v[56:59], v[136:139], v[170:173], 0
	v_mfma_f32_16x16x32_bf16 v[44:47], v[128:131], v[178:181], 0
	v_mfma_f32_16x16x32_bf16 v[40:43], v[136:139], v[178:181], 0
	v_mfma_f32_16x16x32_bf16 v[28:31], v[128:131], v[218:221], 0
	v_mfma_f32_16x16x32_bf16 v[24:27], v[136:139], v[218:221], 0
	v_mfma_f32_16x16x32_bf16 v[12:15], v[128:131], v[226:229], 0
	v_mfma_f32_16x16x32_bf16 v[8:11], v[136:139], v[226:229], 0
	v_mfma_f32_16x16x32_bf16 v[60:63], v[132:135], v[174:177], v[60:63]
	v_mfma_f32_16x16x32_bf16 v[56:59], v[140:143], v[174:177], v[56:59]
	v_mfma_f32_16x16x32_bf16 v[44:47], v[132:135], v[214:217], v[44:47]
	v_mfma_f32_16x16x32_bf16 v[40:43], v[140:143], v[214:217], v[40:43]
	v_mfma_f32_16x16x32_bf16 v[28:31], v[132:135], v[222:225], v[28:31]
	v_mfma_f32_16x16x32_bf16 v[24:27], v[140:143], v[222:225], v[24:27]
	v_mfma_f32_16x16x32_bf16 v[12:15], v[132:135], v[230:233], v[12:15]
	v_mfma_f32_16x16x32_bf16 v[8:11], v[140:143], v[230:233], v[8:11]
	s_setprio 0
	s_setprio 1
	v_mfma_f32_16x16x32_bf16 v[52:55], v[144:147], v[170:173], 0
	v_mfma_f32_16x16x32_bf16 v[48:51], v[152:155], v[170:173], 0
	v_mfma_f32_16x16x32_bf16 v[36:39], v[144:147], v[178:181], 0
	v_mfma_f32_16x16x32_bf16 v[32:35], v[152:155], v[178:181], 0
	v_mfma_f32_16x16x32_bf16 v[20:23], v[144:147], v[218:221], 0
	v_mfma_f32_16x16x32_bf16 v[16:19], v[152:155], v[218:221], 0
	v_mfma_f32_16x16x32_bf16 v[4:7], v[144:147], v[226:229], 0
	v_mfma_f32_16x16x32_bf16 v[0:3], v[152:155], v[226:229], 0
	v_mfma_f32_16x16x32_bf16 v[52:55], v[148:151], v[174:177], v[52:55]
	v_mfma_f32_16x16x32_bf16 v[48:51], v[166:169], v[174:177], v[48:51]
	v_mfma_f32_16x16x32_bf16 v[36:39], v[148:151], v[214:217], v[36:39]
	v_mfma_f32_16x16x32_bf16 v[32:35], v[166:169], v[214:217], v[32:35]
	v_mfma_f32_16x16x32_bf16 v[20:23], v[148:151], v[222:225], v[20:23]
	v_mfma_f32_16x16x32_bf16 v[16:19], v[166:169], v[222:225], v[16:19]
	v_mfma_f32_16x16x32_bf16 v[4:7], v[148:151], v[230:233], v[4:7]
	v_mfma_f32_16x16x32_bf16 v[0:3], v[166:169], v[230:233], v[0:3]
	s_setprio 0
	s_barrier
	s_branch .Lmy_sp3
